# v16 + softmax row-max cross-half exchange via v_permlane32_swap instead of ds_bpermute in the six attention tile loops
# baseline (speedup 1.0000x reference)
.LBB0_1145:
	s_waitcnt lgkmcnt(0)
	v_add_f32_e32 v65, v65, v230
	v_cmp_gt_u32_e32 vcc, s46, v187
	v_add_f32_e32 v48, v48, v229
	v_add_f32_e32 v47, v47, v225
	v_cndmask_b32_e32 v187, v137, v65, vcc
	v_cmp_gt_u32_e32 vcc, s46, v228
	v_add_f32_e32 v46, v46, v221
	v_add_f32_e32 v45, v45, v217
	v_cndmask_b32_e32 v228, v137, v48, vcc
	v_add_f32_e32 v48, v64, v227
	v_cmp_gt_u32_e32 vcc, s46, v226
	v_add_f32_e32 v44, v44, v213
	v_add_f32_e32 v43, v43, v209
	v_cndmask_b32_e32 v226, v137, v48, vcc
	v_cmp_gt_u32_e32 vcc, s46, v224
	v_add_f32_e32 v42, v42, v205
	v_add_f32_e32 v41, v41, v201
	v_cndmask_b32_e32 v224, v137, v47, vcc
	v_add_f32_e32 v47, v63, v223
	v_cmp_gt_u32_e32 vcc, s46, v222
	v_add_f32_e32 v40, v40, v197
	v_add_f32_e32 v39, v39, v193
	v_cndmask_b32_e32 v64, v137, v47, vcc
	v_cmp_gt_u32_e32 vcc, s46, v220
	v_add_f32_e32 v38, v38, v189
	v_add_f32_e32 v37, v37, v183
	v_cndmask_b32_e32 v220, v137, v46, vcc
	v_add_f32_e32 v46, v62, v219
	v_cmp_gt_u32_e32 vcc, s46, v218
	v_add_f32_e32 v36, v36, v179
	v_add_f32_e32 v35, v35, v175
	v_cndmask_b32_e32 v62, v137, v46, vcc
	v_cmp_gt_u32_e32 vcc, s46, v216
	v_add_f32_e32 v34, v34, v171
	v_add_f32_e32 v0, v49, v0
	v_cndmask_b32_e32 v48, v137, v45, vcc
	v_add_f32_e32 v45, v61, v215
	v_cmp_gt_u32_e32 vcc, s46, v214
	s_nop 1
	v_cndmask_b32_e32 v214, v137, v45, vcc
	v_cmp_gt_u32_e32 vcc, s46, v212
	s_nop 1
	v_cndmask_b32_e32 v47, v137, v44, vcc
	v_add_f32_e32 v44, v60, v211
	v_cmp_gt_u32_e32 vcc, s46, v210
	s_nop 1
	v_cndmask_b32_e32 v60, v137, v44, vcc
	v_cmp_gt_u32_e32 vcc, s46, v208
	s_nop 1
	v_cndmask_b32_e32 v45, v137, v43, vcc
	v_add_f32_e32 v43, v59, v207
	v_cmp_gt_u32_e32 vcc, s46, v206
	s_nop 1
	v_cndmask_b32_e32 v206, v137, v43, vcc
	v_cmp_gt_u32_e32 vcc, s46, v204
	s_nop 1
	v_cndmask_b32_e32 v43, v137, v42, vcc
	v_add_f32_e32 v42, v58, v203
	v_cmp_gt_u32_e32 vcc, s46, v202
	s_nop 1
	v_cndmask_b32_e32 v58, v137, v42, vcc
	v_cmp_gt_u32_e32 vcc, s46, v200
	s_nop 1
	v_cndmask_b32_e32 v46, v137, v41, vcc
	v_add_f32_e32 v41, v57, v199
	v_cmp_gt_u32_e32 vcc, s46, v198
	s_nop 1
	v_cndmask_b32_e32 v198, v137, v41, vcc
	v_cmp_gt_u32_e32 vcc, s46, v196
	s_nop 1
	v_cndmask_b32_e32 v44, v137, v40, vcc
	v_add_f32_e32 v40, v56, v195
	v_cmp_gt_u32_e32 vcc, s46, v194
	s_nop 1
	v_cndmask_b32_e32 v56, v137, v40, vcc
	v_cmp_gt_u32_e32 vcc, s46, v192
	s_nop 1
	v_cndmask_b32_e32 v42, v137, v39, vcc
	v_add_f32_e32 v39, v55, v191
	v_cmp_gt_u32_e32 vcc, s46, v190
	s_nop 1
	v_cndmask_b32_e32 v55, v137, v39, vcc
	v_cmp_gt_u32_e32 vcc, s46, v188
	s_nop 1
	v_cndmask_b32_e32 v41, v137, v38, vcc
	v_add_f32_e32 v38, v54, v185
	v_cmp_gt_u32_e32 vcc, s46, v184
	s_nop 1
	v_cndmask_b32_e32 v61, v137, v38, vcc
	v_cmp_gt_u32_e32 vcc, s46, v182
	v_add_f32_e32 v38, v53, v181
	s_nop 0
	v_cndmask_b32_e32 v37, v137, v37, vcc
	v_cmp_gt_u32_e32 vcc, s46, v180
	s_nop 1
	v_cndmask_b32_e32 v40, v137, v38, vcc
	v_cmp_gt_u32_e32 vcc, s46, v178
	v_add_f32_e32 v38, v52, v177
	s_nop 0
	v_cndmask_b32_e32 v36, v137, v36, vcc
	v_cmp_gt_u32_e32 vcc, s46, v176
	s_nop 1
	v_cndmask_b32_e32 v39, v137, v38, vcc
	v_cmp_gt_u32_e32 vcc, s46, v174
	s_nop 1
	v_cndmask_b32_e32 v38, v137, v35, vcc
	v_add_f32_e32 v35, v51, v173
	v_cmp_gt_u32_e32 vcc, s46, v172
	s_nop 1
	v_cndmask_b32_e32 v52, v137, v35, vcc
	v_cmp_gt_u32_e32 vcc, s46, v170
	s_nop 1
	v_cndmask_b32_e32 v35, v137, v34, vcc
	v_add_f32_e32 v34, v50, v169
	v_cmp_gt_u32_e32 vcc, s46, v168
	s_nop 1
	v_cndmask_b32_e32 v50, v137, v34, vcc
	v_max3_f32 v34, v137, v50, v35
	v_cmp_gt_u32_e32 vcc, s46, v186
	v_max3_f32 v34, v34, v52, v38
	v_max3_f32 v34, v34, v39, v36
	v_max3_f32 v34, v34, v40, v37
	v_cndmask_b32_e32 v0, v137, v0, vcc
	v_max3_f32 v34, v34, v61, v41
	v_max3_f32 v34, v34, v55, v42
	v_max3_f32 v34, v34, v56, v44
	v_max3_f32 v34, v34, v198, v46
	v_max3_f32 v34, v34, v58, v43
	v_max3_f32 v34, v34, v206, v45
	v_max3_f32 v34, v34, v60, v47
	v_max3_f32 v34, v34, v214, v48
	v_max3_f32 v34, v34, v62, v220
	v_max3_f32 v34, v34, v64, v224
	v_max3_f32 v34, v34, v226, v228
	v_max3_f32 v34, v34, v187, v0
	v_mov_b32_e32 v49, v34
	s_nop 1
	v_permlane32_swap_b32 v49, v34
	v_max_f32_e32 v34, v34, v34
	s_waitcnt lgkmcnt(0)
	v_max_f32_e32 v49, v49, v49
	v_max_f32_e32 v171, v34, v49
	v_max_f32_e32 v34, v166, v166
	v_max_f32_e32 v34, v34, v171
	v_sub_f32_e32 v49, v50, v34
	v_sub_f32_e32 v35, v35, v34
	v_exp_f32_e32 v51, v49
	v_exp_f32_e32 v35, v35
	v_sub_f32_e32 v49, v52, v34
	v_sub_f32_e32 v38, v38, v34
	v_exp_f32_e32 v54, v49
	v_exp_f32_e32 v38, v38
	v_sub_f32_e32 v39, v39, v34
	v_sub_f32_e32 v36, v36, v34
	v_add_f32_e32 v49, v51, v35
	v_exp_f32_e32 v57, v39
	v_exp_f32_e32 v39, v36
	v_sub_f32_e32 v36, v40, v34
	v_add_f32_e32 v49, 0, v49
	v_add_f32_e32 v50, v54, v38
	v_exp_f32_e32 v59, v36
	v_sub_f32_e32 v36, v37, v34
	v_exp_f32_e32 v40, v36
	v_add_f32_e32 v36, v50, v49
	v_sub_f32_e32 v49, v61, v34
	v_exp_f32_e32 v61, v49
	v_sub_f32_e32 v41, v41, v34
	v_sub_f32_e32 v49, v55, v34
	v_exp_f32_e32 v41, v41
	v_exp_f32_e32 v63, v49
	v_sub_f32_e32 v42, v42, v34
	v_sub_f32_e32 v49, v56, v34
	v_exp_f32_e32 v42, v42
	v_exp_f32_e32 v65, v49
	v_sub_f32_e32 v44, v44, v34
	v_sub_f32_e32 v49, v198, v34
	v_add_f32_e32 v37, v57, v39
	v_exp_f32_e32 v44, v44
	v_exp_f32_e32 v169, v49
	v_sub_f32_e32 v46, v46, v34
	v_sub_f32_e32 v49, v58, v34
	v_add_f32_e32 v36, v37, v36
	v_add_f32_e32 v37, v59, v40
	v_exp_f32_e32 v46, v46
	v_exp_f32_e32 v52, v49
	v_sub_f32_e32 v43, v43, v34
	v_sub_f32_e32 v49, v206, v34
	v_add_f32_e32 v36, v37, v36
	v_add_f32_e32 v37, v61, v41
	v_exp_f32_e32 v43, v43
	v_exp_f32_e32 v55, v49
	v_sub_f32_e32 v45, v45, v34
	v_sub_f32_e32 v49, v60, v34
	v_add_f32_e32 v36, v37, v36
	v_add_f32_e32 v37, v63, v42
	v_exp_f32_e32 v45, v45
	v_exp_f32_e32 v58, v49
	v_sub_f32_e32 v47, v47, v34
	v_sub_f32_e32 v49, v214, v34
	v_add_f32_e32 v36, v37, v36
	v_add_f32_e32 v37, v65, v44
	v_exp_f32_e32 v47, v47
	v_exp_f32_e32 v60, v49
	v_sub_f32_e32 v48, v48, v34
	v_sub_f32_e32 v49, v62, v34
	v_add_f32_e32 v36, v37, v36
	v_add_f32_e32 v37, v169, v46
	v_exp_f32_e32 v48, v48
	v_exp_f32_e32 v62, v49
	v_sub_f32_e32 v49, v220, v34
	v_sub_f32_e32 v50, v64, v34
	v_add_f32_e32 v36, v37, v36
	v_add_f32_e32 v37, v52, v43
	v_exp_f32_e32 v49, v49
	v_exp_f32_e32 v64, v50
	v_sub_f32_e32 v50, v224, v34
	v_sub_f32_e32 v53, v226, v34
	v_add_f32_e32 v36, v37, v36
	v_add_f32_e32 v37, v55, v45
	v_exp_f32_e32 v50, v50
	v_exp_f32_e32 v168, v53
	v_sub_f32_e32 v53, v228, v34
	v_add_f32_e32 v36, v37, v36
	v_add_f32_e32 v37, v58, v47
	v_exp_f32_e32 v53, v53
	v_sub_f32_e32 v56, v187, v34
	v_sub_f32_e32 v0, v0, v34
	v_add_f32_e32 v36, v37, v36
	v_add_f32_e32 v37, v60, v48
	v_exp_f32_e32 v170, v56
	v_exp_f32_e32 v56, v0
	v_add_f32_e32 v36, v37, v36
	v_add_f32_e32 v37, v62, v49
	v_add_f32_e32 v36, v37, v36
	v_add_f32_e32 v37, v64, v50
	v_add_f32_e32 v0, v37, v36
	v_add_f32_e32 v36, v168, v53
	v_add_f32_e32 v0, v36, v0
	v_add_f32_e32 v36, v170, v56
	v_add_f32_e32 v36, v36, v0
	v_sub_f32_e32 v172, v166, v34
	ds_bpermute_b32 v37, v161, v36
	v_exp_f32_e32 v0, v172
	v_cmp_gt_f32_e32 vcc, v171, v166
	s_cbranch_vccz .LBB0_1147
	v_pk_mul_f32 v[32:33], v[32:33], v[0:1] op_sel_hi:[1,0]
	v_pk_mul_f32 v[30:31], v[30:31], v[0:1] op_sel_hi:[1,0]
	v_pk_mul_f32 v[28:29], v[28:29], v[0:1] op_sel_hi:[1,0]
	v_pk_mul_f32 v[26:27], v[26:27], v[0:1] op_sel_hi:[1,0]
	v_pk_mul_f32 v[24:25], v[24:25], v[0:1] op_sel_hi:[1,0]
	v_pk_mul_f32 v[22:23], v[22:23], v[0:1] op_sel_hi:[1,0]
	v_pk_mul_f32 v[20:21], v[20:21], v[0:1] op_sel_hi:[1,0]
	v_pk_mul_f32 v[18:19], v[18:19], v[0:1] op_sel_hi:[1,0]
	v_pk_mul_f32 v[16:17], v[16:17], v[0:1] op_sel_hi:[1,0]
	v_pk_mul_f32 v[14:15], v[14:15], v[0:1] op_sel_hi:[1,0]
	v_pk_mul_f32 v[12:13], v[12:13], v[0:1] op_sel_hi:[1,0]
	v_pk_mul_f32 v[10:11], v[10:11], v[0:1] op_sel_hi:[1,0]
	v_pk_mul_f32 v[8:9], v[8:9], v[0:1] op_sel_hi:[1,0]
	v_pk_mul_f32 v[6:7], v[6:7], v[0:1] op_sel_hi:[1,0]
	v_pk_mul_f32 v[4:5], v[4:5], v[0:1] op_sel_hi:[1,0]
	v_pk_mul_f32 v[2:3], v[2:3], v[0:1] op_sel_hi:[1,0]

.LBB0_1252:
	s_or_b64 exec, exec, s[8:9]
	s_lshl_b32 s8, s7, 3
	s_or_b32 s8, s8, s56
	s_bfe_u32 s66, s8, 0x30001
	v_ashrrev_i32_e32 v86, 3, v87
	v_lshl_add_u32 v2, s66, 7, v86
	v_lshlrev_b32_e32 v0, 4, v84
	v_ashrrev_i32_e32 v3, 31, v2
	v_and_b32_e32 v131, 0x70, v0
	v_lshlrev_b64 v[10:11], 8, v[2:3]
	s_lshl_b32 s46, s6, 1
	v_or3_b32 v10, v131, s46, v10
	s_mov_b64 s[8:9], 0x4000
	v_lshl_add_u64 v[2:3], s[58:59], 0, v[10:11]
	v_lshl_add_u64 v[6:7], s[60:61], 0, v[10:11]
	v_lshl_add_u64 v[10:11], v[10:11], 0, s[8:9]
	v_lshl_add_u64 v[12:13], s[58:59], 0, v[10:11]
	v_lshl_add_u64 v[14:15], s[60:61], 0, v[10:11]
	global_load_dwordx4 v[2:5], v[2:3], off
	s_nop 0
	global_load_dwordx4 v[6:9], v[6:7], off
	s_nop 0
	global_load_dwordx4 v[10:13], v[12:13], off
	s_nop 0
	global_load_dwordx4 v[14:17], v[14:15], off
	s_lshl_b32 s7, s7, 4
	s_andn2_b32 s7, s7, 31
	s_sub_i32 s16, 0x7e0, s7
	v_and_b32_e32 v85, 31, v84
	v_or_b32_e32 v193, s16, v85
	v_ashrrev_i32_e32 v0, 5, v84
	v_lshl_add_u32 v132, s66, 11, v193
	v_mov_b64_e32 v[18:19], s[50:51]
	v_mad_i64_i32 v[82:83], s[8:9], v132, s84, v[18:19]
	s_lshl_b32 s72, s34, 1
	s_mov_b32 s73, s67
	v_lshlrev_b32_e32 v20, 3, v0
	v_lshl_add_u64 v[18:19], v[82:83], 0, s[72:73]
	v_ashrrev_i32_e32 v21, 31, v20
	v_lshl_add_u64 v[18:19], v[20:21], 1, v[18:19]
	global_load_dwordx4 v[98:101], v[18:19], off offset:2560
	global_load_dwordx4 v[102:105], v[18:19], off offset:2592
	global_load_dwordx4 v[106:109], v[18:19], off offset:2624
	global_load_dwordx4 v[110:113], v[18:19], off offset:2656
	v_lshrrev_b32_e32 v18, 2, v84
	v_lshlrev_b32_e32 v130, 2, v0
	v_mul_lo_u32 v194, v86, s86
	v_mul_lo_u32 v21, v86, 48
	v_and_or_b32 v22, v18, 3, v130
	v_add_u32_e32 v18, 0, v194
	v_lshlrev_b32_e32 v19, 1, v84
	v_add_u32_e32 v135, v18, v131
	v_add_u32_e32 v18, v18, v21
	s_movk_i32 s8, 0xffd0
	v_and_b32_e32 v20, 32, v19
	v_mad_u32_u24 v19, v85, s86, 0
	v_lshlrev_b32_e32 v195, 4, v0
	v_add_u32_e32 v134, v18, v131
	v_add_u32_e32 v42, v19, v195
	v_mad_u64_u32 v[18:19], s[8:9], v86, s8, v[134:135]
	v_add_u32_e32 v19, v18, v21
	s_waitcnt vmcnt(7)
	ds_write_b128 v135, v[2:5]
	s_waitcnt vmcnt(6)
	ds_write_b128 v134, v[6:9] offset:9216
	s_waitcnt vmcnt(5)
	ds_write_b128 v18, v[10:13] offset:21504
	s_waitcnt vmcnt(4)
	ds_write_b128 v19, v[14:17] offset:30720
	v_mov_b32_e32 v242, 0x1affc
	v_mov_b32_e32 v243, 0xf149f2ca
	ds_write_b32 v242, v243
	s_waitcnt lgkmcnt(0)
	s_barrier
	ds_read_b128 v[2:5], v42
	ds_read_b128 v[34:37], v42 offset:32
	ds_read_b128 v[6:9], v42 offset:4608
	ds_read_b128 v[38:41], v42 offset:4640
	ds_read_b128 v[44:47], v42 offset:64
	ds_read_b128 v[48:51], v42 offset:96
	ds_read_b128 v[52:55], v42 offset:4672
	ds_read_b128 v[56:59], v42 offset:4704
	v_lshlrev_b32_e32 v10, 3, v84
	v_and_b32_e32 v10, 24, v10
	v_mul_lo_u32 v11, v22, s85
	v_or3_b32 v196, v11, v20, v10
	s_waitcnt vmcnt(3) lgkmcnt(7)
	v_mfma_f32_32x32x16_bf16 v[18:33], v[2:5], v[98:101], 0
	s_waitcnt lgkmcnt(5)
	v_mfma_f32_32x32x16_bf16 v[2:17], v[6:9], v[98:101], 0
	s_waitcnt vmcnt(2)
	v_mfma_f32_32x32x16_bf16 v[18:33], v[34:37], v[102:105], v[18:33]
	s_waitcnt lgkmcnt(4)
	v_mfma_f32_32x32x16_bf16 v[2:17], v[38:41], v[102:105], v[2:17]
	s_waitcnt vmcnt(1) lgkmcnt(3)
	v_mfma_f32_32x32x16_bf16 v[18:33], v[44:47], v[106:109], v[18:33]
	v_add_u32_e32 v89, 0, v196
	ds_read_b64_tr_b16 v[34:35], v89 offset:9216
	ds_read_b64_tr_b16 v[36:37], v89 offset:10752
	ds_read_b64_tr_b16 v[40:41], v89 offset:10816
	ds_read_b64_tr_b16 v[38:39], v89 offset:9280
	v_subrev_u32_e32 v88, 31, v193
	v_lshlrev_b32_e32 v45, 6, v0
	v_sub_u32_e32 v46, v88, v45
	v_cmp_lt_i32_e32 vcc, -1, v46
	v_cmp_gt_i32_e64 s[8:9], 32, v0
	s_waitcnt lgkmcnt(5)
	v_mfma_f32_32x32x16_bf16 v[2:17], v[52:55], v[106:109], v[2:17]
	s_and_b64 s[10:11], s[8:9], vcc
	v_mov_b32_e32 v43, 0xf149f2ca
	v_mov_b32_e32 v44, 0xf149f2ca
	s_waitcnt vmcnt(0)
	s_add_i32 s100, s70, 0x1800
	s_mov_b32 s101, 0
	v_lshl_add_u64 v[244:245], v[82:83], 0, s[100:101]
	global_load_ushort v246, v[244:245], off
	v_mfma_f32_32x32x16_bf16 v[18:33], v[48:51], v[110:113], v[18:33]
	s_waitcnt lgkmcnt(4)
	v_mfma_f32_32x32x16_bf16 v[2:17], v[56:59], v[110:113], v[2:17]
	v_min_u32_e32 v210, 0x7f, v46
	v_lshl_add_u32 v210, v210, 2, s3
	v_cndmask_b32_e64 v210, v242, v210, s[10:11]
	ds_read_b32 v210, v210
	v_sub_u32_e32 v74, v193, v45
	v_add_u32_e32 v150, 0xfffffde1, v74
	v_cmp_lt_i32_e64 s[8:9], -1, v150
	v_cmp_gt_i32_e32 vcc, 24, v0
	s_and_b64 s[10:11], vcc, s[8:9]
	v_min_u32_e32 v211, 0x7f, v150
	v_lshl_add_u32 v211, v211, 2, s3
	v_cndmask_b32_e64 v211, v242, v211, s[10:11]
	ds_read_b32 v211, v211
	v_or_b32_e32 v151, 1, v130
	v_lshlrev_b32_e32 v152, 4, v151
	v_sub_u32_e32 v45, v88, v152
	v_cmp_lt_i32_e64 s[8:9], -1, v45
	v_cmp_gt_i32_e64 s[10:11], s82, v151
	s_and_b64 s[10:11], s[10:11], s[8:9]
	v_min_u32_e32 v212, 0x7f, v45
	v_lshl_add_u32 v212, v212, 2, s3
	v_cndmask_b32_e64 v212, v242, v212, s[10:11]
	ds_read_b32 v212, v212
	v_add_u32_e32 v153, 0xfffffdd1, v74
	v_cmp_lt_i32_e64 s[8:9], -1, v153
	s_and_b64 s[10:11], vcc, s[8:9]
	v_min_u32_e32 v213, 0x7f, v153
	v_lshl_add_u32 v213, v213, 2, s3
	v_cndmask_b32_e64 v213, v242, v213, s[10:11]
	ds_read_b32 v213, v213
	v_or_b32_e32 v154, 2, v130
	v_lshlrev_b32_e32 v155, 4, v154
	v_sub_u32_e32 v45, v88, v155
	v_cmp_lt_i32_e64 s[8:9], -1, v45
	v_cmp_gt_i32_e64 s[10:11], s82, v154
	s_and_b64 s[10:11], s[10:11], s[8:9]
	v_min_u32_e32 v214, 0x7f, v45
	v_lshl_add_u32 v214, v214, 2, s3
	v_cndmask_b32_e64 v214, v242, v214, s[10:11]
	ds_read_b32 v214, v214
	v_add_u32_e32 v156, 0xfffffdc1, v74
	v_cmp_lt_i32_e64 s[8:9], -1, v156
	s_and_b64 s[10:11], vcc, s[8:9]
	v_min_u32_e32 v215, 0x7f, v156
	v_lshl_add_u32 v215, v215, 2, s3
	v_cndmask_b32_e64 v215, v242, v215, s[10:11]
	ds_read_b32 v215, v215
	v_or_b32_e32 v157, 3, v130
	v_lshlrev_b32_e32 v158, 4, v157
	v_sub_u32_e32 v45, v88, v158
	v_cmp_lt_i32_e32 vcc, -1, v45
	v_cmp_gt_i32_e64 s[8:9], s82, v157
	s_and_b64 s[10:11], s[8:9], vcc
	v_min_u32_e32 v216, 0x7f, v45
	v_lshl_add_u32 v216, v216, 2, s3
	v_cndmask_b32_e64 v216, v242, v216, s[10:11]
	ds_read_b32 v216, v216
	v_add_u32_e32 v159, 0xfffffdb1, v74
	v_cmp_lt_i32_e32 vcc, -1, v159
	v_cmp_gt_i32_e64 s[8:9], 23, v0
	s_and_b64 s[10:11], s[8:9], vcc
	v_min_u32_e32 v217, 0x7f, v159
	v_lshl_add_u32 v217, v217, 2, s3
	v_cndmask_b32_e64 v217, v242, v217, s[10:11]
	ds_read_b32 v217, v217
	v_add_u32_e32 v45, 0xffffff61, v74
	v_cmp_lt_i32_e64 s[8:9], -1, v45
	v_cmp_gt_i32_e32 vcc, 30, v0
	s_and_b64 s[10:11], vcc, s[8:9]
	v_min_u32_e32 v218, 0x7f, v45
	v_lshl_add_u32 v218, v218, 2, s3
	v_cndmask_b32_e64 v218, v242, v218, s[10:11]
	ds_read_b32 v218, v218
	v_add_u32_e32 v160, 0xfffffd61, v74
	v_cmp_lt_i32_e64 s[10:11], -1, v160
	v_cmp_gt_i32_e64 s[8:9], 22, v0
	s_and_b64 s[12:13], s[8:9], s[10:11]
	v_min_u32_e32 v219, 0x7f, v160
	v_lshl_add_u32 v219, v219, 2, s3
	v_cndmask_b32_e64 v219, v242, v219, s[12:13]
	ds_read_b32 v219, v219
	v_add_u32_e32 v45, 0xffffff51, v74
	v_cmp_lt_i32_e64 s[10:11], -1, v45
	s_and_b64 s[12:13], vcc, s[10:11]
	v_min_u32_e32 v220, 0x7f, v45
	v_lshl_add_u32 v220, v220, 2, s3
	v_cndmask_b32_e64 v220, v242, v220, s[12:13]
	ds_read_b32 v220, v220
	v_add_u32_e32 v161, 0xfffffd51, v74
	v_cmp_lt_i32_e64 s[10:11], -1, v161
	s_and_b64 s[12:13], s[8:9], s[10:11]
	v_min_u32_e32 v221, 0x7f, v161
	v_lshl_add_u32 v221, v221, 2, s3
	v_cndmask_b32_e64 v221, v242, v221, s[12:13]
	ds_read_b32 v221, v221
	v_add_u32_e32 v45, 0xffffff41, v74
	v_cmp_lt_i32_e64 s[10:11], -1, v45
	s_and_b64 s[12:13], vcc, s[10:11]
	v_min_u32_e32 v222, 0x7f, v45
	v_lshl_add_u32 v222, v222, 2, s3
	v_cndmask_b32_e64 v222, v242, v222, s[12:13]
	ds_read_b32 v222, v222
	v_add_u32_e32 v162, 0xfffffd41, v74
	v_cmp_lt_i32_e32 vcc, -1, v162
	s_and_b64 s[10:11], s[8:9], vcc
	v_min_u32_e32 v223, 0x7f, v162
	v_lshl_add_u32 v223, v223, 2, s3
	v_cndmask_b32_e64 v223, v242, v223, s[10:11]
	ds_read_b32 v223, v223
	v_add_u32_e32 v45, 0xffffff31, v74
	v_cmp_lt_i32_e32 vcc, -1, v45
	v_cmp_gt_i32_e64 s[8:9], 29, v0
	s_and_b64 s[10:11], s[8:9], vcc
	v_min_u32_e32 v224, 0x7f, v45
	v_lshl_add_u32 v224, v224, 2, s3
	v_cndmask_b32_e64 v224, v242, v224, s[10:11]
	ds_read_b32 v224, v224
	v_add_u32_e32 v163, 0xfffffd31, v74
	v_cmp_lt_i32_e32 vcc, -1, v163
	v_cmp_gt_i32_e64 s[8:9], 21, v0
	s_and_b64 s[10:11], s[8:9], vcc
	v_min_u32_e32 v225, 0x7f, v163
	v_lshl_add_u32 v225, v225, 2, s3
	v_cndmask_b32_e64 v225, v242, v225, s[10:11]
	ds_read_b32 v225, v225
	v_add_u32_e32 v45, 0xfffffee1, v74
	v_cmp_lt_i32_e64 s[8:9], -1, v45
	v_cmp_gt_i32_e32 vcc, 28, v0
	s_and_b64 s[10:11], vcc, s[8:9]
	v_min_u32_e32 v226, 0x7f, v45
	v_lshl_add_u32 v226, v226, 2, s3
	v_cndmask_b32_e64 v226, v242, v226, s[10:11]
	ds_read_b32 v226, v226
	v_add_u32_e32 v164, 0xfffffce1, v74
	v_cmp_lt_i32_e64 s[10:11], -1, v164
	v_cmp_gt_i32_e64 s[8:9], 20, v0
	s_and_b64 s[12:13], s[8:9], s[10:11]
	v_min_u32_e32 v227, 0x7f, v164
	v_lshl_add_u32 v227, v227, 2, s3
	v_cndmask_b32_e64 v227, v242, v227, s[12:13]
	ds_read_b32 v227, v227
	v_add_u32_e32 v45, 0xfffffed1, v74
	v_cmp_lt_i32_e64 s[10:11], -1, v45
	s_and_b64 s[12:13], vcc, s[10:11]
	v_min_u32_e32 v228, 0x7f, v45
	v_lshl_add_u32 v228, v228, 2, s3
	v_cndmask_b32_e64 v228, v242, v228, s[12:13]
	ds_read_b32 v228, v228
	v_add_u32_e32 v165, 0xfffffcd1, v74
	v_cmp_lt_i32_e64 s[10:11], -1, v165
	s_and_b64 s[12:13], s[8:9], s[10:11]
	v_min_u32_e32 v229, 0x7f, v165
	v_lshl_add_u32 v229, v229, 2, s3
	v_cndmask_b32_e64 v229, v242, v229, s[12:13]
	ds_read_b32 v229, v229
	v_add_u32_e32 v45, 0xfffffec1, v74
	v_cmp_lt_i32_e64 s[10:11], -1, v45
	s_and_b64 s[12:13], vcc, s[10:11]
	v_min_u32_e32 v230, 0x7f, v45
	v_lshl_add_u32 v230, v230, 2, s3
	v_cndmask_b32_e64 v230, v242, v230, s[12:13]
	ds_read_b32 v230, v230
	v_add_u32_e32 v166, 0xfffffcc1, v74
	v_cmp_lt_i32_e32 vcc, -1, v166
	s_and_b64 s[10:11], s[8:9], vcc
	v_min_u32_e32 v231, 0x7f, v166
	v_lshl_add_u32 v231, v231, 2, s3
	v_cndmask_b32_e64 v231, v242, v231, s[10:11]
	ds_read_b32 v231, v231
	v_add_u32_e32 v45, 0xfffffeb1, v74
	v_cmp_lt_i32_e32 vcc, -1, v45
	v_cmp_gt_i32_e64 s[8:9], 27, v0
	s_and_b64 s[10:11], s[8:9], vcc
	v_min_u32_e32 v232, 0x7f, v45
	v_lshl_add_u32 v232, v232, 2, s3
	v_cndmask_b32_e64 v232, v242, v232, s[10:11]
	ds_read_b32 v232, v232
	v_add_u32_e32 v167, 0xfffffcb1, v74
	v_cmp_lt_i32_e32 vcc, -1, v167
	v_cmp_gt_i32_e64 s[8:9], 19, v0
	s_and_b64 s[10:11], s[8:9], vcc
	v_min_u32_e32 v233, 0x7f, v167
	v_lshl_add_u32 v233, v233, 2, s3
	v_cndmask_b32_e64 v233, v242, v233, s[10:11]
	ds_read_b32 v233, v233
	v_add_u32_e32 v45, 0xfffffe61, v74
	v_cmp_lt_i32_e64 s[8:9], -1, v45
	v_cmp_gt_i32_e32 vcc, 26, v0
	s_and_b64 s[10:11], vcc, s[8:9]
	v_min_u32_e32 v234, 0x7f, v45
	v_lshl_add_u32 v234, v234, 2, s3
	v_cndmask_b32_e64 v234, v242, v234, s[10:11]
	ds_read_b32 v234, v234
	v_add_u32_e32 v168, 0xfffffc61, v74
	v_cmp_lt_i32_e64 s[10:11], -1, v168
	v_cmp_gt_i32_e64 s[8:9], 18, v0
	s_and_b64 s[12:13], s[8:9], s[10:11]
	v_min_u32_e32 v235, 0x7f, v168
	v_lshl_add_u32 v235, v235, 2, s3
	v_cndmask_b32_e64 v235, v242, v235, s[12:13]
	ds_read_b32 v235, v235
	v_add_u32_e32 v45, 0xfffffe51, v74
	v_cmp_lt_i32_e64 s[10:11], -1, v45
	s_and_b64 s[12:13], vcc, s[10:11]
	v_min_u32_e32 v236, 0x7f, v45
	v_lshl_add_u32 v236, v236, 2, s3
	v_cndmask_b32_e64 v236, v242, v236, s[12:13]
	ds_read_b32 v236, v236
	v_add_u32_e32 v169, 0xfffffc51, v74
	v_cmp_lt_i32_e64 s[10:11], -1, v169
	s_and_b64 s[12:13], s[8:9], s[10:11]
	v_min_u32_e32 v237, 0x7f, v169
	v_lshl_add_u32 v237, v237, 2, s3
	v_cndmask_b32_e64 v237, v242, v237, s[12:13]
	ds_read_b32 v237, v237
	v_add_u32_e32 v45, 0xfffffe41, v74
	v_cmp_lt_i32_e64 s[10:11], -1, v45
	s_and_b64 s[12:13], vcc, s[10:11]
	v_min_u32_e32 v238, 0x7f, v45
	v_lshl_add_u32 v238, v238, 2, s3
	v_cndmask_b32_e64 v238, v242, v238, s[12:13]
	ds_read_b32 v238, v238
	v_add_u32_e32 v170, 0xfffffc41, v74
	v_cmp_lt_i32_e32 vcc, -1, v170
	s_and_b64 s[10:11], s[8:9], vcc
	v_min_u32_e32 v239, 0x7f, v170
	v_lshl_add_u32 v239, v239, 2, s3
	v_cndmask_b32_e64 v239, v242, v239, s[10:11]
	ds_read_b32 v239, v239
	v_add_u32_e32 v45, 0xfffffe31, v74
	v_cmp_lt_i32_e32 vcc, -1, v45
	v_cmp_gt_i32_e64 s[8:9], 25, v0
	s_and_b64 s[10:11], s[8:9], vcc
	v_min_u32_e32 v240, 0x7f, v45
	v_lshl_add_u32 v240, v240, 2, s3
	v_cndmask_b32_e64 v240, v242, v240, s[10:11]
	ds_read_b32 v240, v240
	v_add_u32_e32 v171, 0xfffffc31, v74
	v_cmp_lt_i32_e32 vcc, -1, v171
	v_cmp_gt_i32_e64 s[8:9], 17, v0
	s_and_b64 s[10:11], s[8:9], vcc
	v_min_u32_e32 v241, 0x7f, v171
	v_lshl_add_u32 v241, v241, 2, s3
	v_cndmask_b32_e64 v241, v242, v241, s[10:11]
	ds_read_b32 v241, v241
	s_waitcnt lgkmcnt(0)
	v_add_f32_e32 v44, v18, v210
	v_add_f32_e32 v43, v2, v211
	v_add_f32_e32 v18, v19, v212
	v_add_f32_e32 v2, v3, v213
	v_add_f32_e32 v19, v20, v214
	v_add_f32_e32 v3, v4, v215
	v_add_f32_e32 v20, v21, v216
	v_add_f32_e32 v4, v5, v217
	v_add_f32_e32 v21, v22, v218
	v_add_f32_e32 v5, v6, v219
	v_add_f32_e32 v22, v23, v220
	v_add_f32_e32 v6, v7, v221
	v_add_f32_e32 v23, v24, v222
	v_add_f32_e32 v7, v8, v223
	v_add_f32_e32 v24, v25, v224
	v_add_f32_e32 v8, v9, v225
	v_add_f32_e32 v25, v26, v226
	v_add_f32_e32 v9, v10, v227
	v_add_f32_e32 v26, v27, v228
	v_add_f32_e32 v10, v11, v229
	v_add_f32_e32 v27, v28, v230
	v_add_f32_e32 v11, v12, v231
	v_add_f32_e32 v28, v29, v232
	v_add_f32_e32 v12, v13, v233
	v_add_f32_e32 v29, v30, v234
	v_add_f32_e32 v13, v14, v235
	v_add_f32_e32 v30, v31, v236
	v_add_f32_e32 v14, v15, v237
	v_add_f32_e32 v31, v32, v238
	v_add_f32_e32 v15, v16, v239
	v_add_f32_e32 v32, v33, v240
	v_add_f32_e32 v16, v17, v241
	v_max3_f32 v17, v191, v44, v43
	v_lshlrev_b32_e32 v33, 7, v0
	v_max3_f32 v17, v17, v18, v2
	v_lshlrev_b32_e32 v45, 2, v85
	v_max3_f32 v17, v17, v19, v3
	s_movk_i32 s8, 0x80
	v_max3_f32 v17, v17, v20, v4
	v_bitop3_b32 v197, v33, s8, v45 bitop3:0x36
	v_max3_f32 v17, v17, v21, v5
	v_mov_b32_e32 v79, 0xf149f2ca
	v_max3_f32 v17, v17, v22, v6
	v_max3_f32 v17, v17, v23, v7
	v_max3_f32 v17, v17, v24, v8
	v_max3_f32 v17, v17, v25, v9
	v_max3_f32 v17, v17, v26, v10
	v_max3_f32 v17, v17, v27, v11
	v_max3_f32 v17, v17, v28, v12
	v_max3_f32 v17, v17, v29, v13
	v_max3_f32 v17, v17, v30, v14
	v_max3_f32 v17, v17, v31, v15
	v_max3_f32 v17, v17, v32, v16
	v_mov_b32_e32 v33, v17
	s_nop 1
	v_permlane32_swap_b32 v33, v17
	v_max_f32_e32 v17, v17, v17
	s_waitcnt lgkmcnt(0)
	v_max_f32_e32 v33, v33, v33
	v_max_f32_e32 v17, v17, v33
	v_max_f32_e32 v75, 0xf149f2ca, v17
	v_sub_f32_e32 v5, v5, v75
	v_exp_f32_e32 v59, v5
	v_sub_f32_e32 v5, v22, v75
	v_exp_f32_e32 v22, v5
	v_sub_f32_e32 v5, v6, v75
	v_exp_f32_e32 v60, v5
	v_sub_f32_e32 v5, v23, v75
	v_exp_f32_e32 v23, v5
	v_sub_f32_e32 v5, v7, v75
	v_sub_f32_e32 v33, v44, v75
	v_sub_f32_e32 v43, v43, v75
	v_exp_f32_e32 v61, v5
	v_sub_f32_e32 v5, v24, v75
	v_exp_f32_e32 v33, v33
	v_exp_f32_e32 v43, v43
	v_sub_f32_e32 v18, v18, v75
	v_sub_f32_e32 v2, v2, v75
	v_sub_f32_e32 v3, v3, v75
	v_exp_f32_e32 v24, v5
	v_sub_f32_e32 v5, v8, v75
	v_exp_f32_e32 v18, v18
	v_exp_f32_e32 v56, v2
	v_sub_f32_e32 v19, v19, v75
	v_exp_f32_e32 v57, v3
	v_sub_f32_e32 v3, v20, v75
	v_exp_f32_e32 v62, v5
	v_sub_f32_e32 v5, v25, v75
	v_exp_f32_e32 v19, v19
	v_exp_f32_e32 v20, v3
	v_sub_f32_e32 v3, v4, v75
	v_exp_f32_e32 v63, v5
	v_sub_f32_e32 v5, v9, v75
	v_exp_f32_e32 v58, v3
	v_sub_f32_e32 v21, v21, v75
	v_exp_f32_e32 v64, v5
	v_sub_f32_e32 v5, v26, v75
	v_add_f32_e32 v44, v33, v43
	v_exp_f32_e32 v21, v21
	v_exp_f32_e32 v65, v5
	v_sub_f32_e32 v5, v10, v75
	v_add_f32_e32 v44, 0, v44
	v_add_f32_e32 v45, v18, v56
	v_exp_f32_e32 v66, v5
	v_sub_f32_e32 v5, v27, v75
	v_add_f32_e32 v3, v45, v44
	v_add_f32_e32 v4, v19, v57
	v_exp_f32_e32 v67, v5
	v_sub_f32_e32 v5, v11, v75
	v_add_f32_e32 v3, v4, v3
	v_add_f32_e32 v4, v20, v58
	v_exp_f32_e32 v68, v5
	v_sub_f32_e32 v5, v28, v75
	v_add_f32_e32 v3, v4, v3
	v_add_f32_e32 v4, v21, v59
	v_exp_f32_e32 v69, v5
	v_sub_f32_e32 v5, v12, v75
	v_add_f32_e32 v3, v4, v3
	v_add_f32_e32 v4, v22, v60
	v_exp_f32_e32 v70, v5
	v_sub_f32_e32 v5, v29, v75
	v_add_f32_e32 v3, v4, v3
	v_add_f32_e32 v4, v23, v61
	v_exp_f32_e32 v71, v5
	v_sub_f32_e32 v5, v13, v75
	v_add_f32_e32 v3, v4, v3
	v_add_f32_e32 v4, v24, v62
	v_exp_f32_e32 v72, v5
	v_sub_f32_e32 v5, v30, v75
	v_add_f32_e32 v3, v4, v3
	v_add_f32_e32 v4, v63, v64
	v_exp_f32_e32 v73, v5
	v_sub_f32_e32 v5, v14, v75
	v_add_f32_e32 v3, v4, v3
	v_add_f32_e32 v4, v65, v66
	v_exp_f32_e32 v80, v5
	v_add_f32_e32 v3, v4, v3
	v_add_f32_e32 v4, v67, v68
	v_add_f32_e32 v3, v4, v3
	v_add_f32_e32 v4, v69, v70
	v_add_f32_e32 v3, v4, v3
	v_add_f32_e32 v4, v71, v72
	v_add_f32_e32 v3, v4, v3
	v_add_f32_e32 v4, v73, v80
	v_add_f32_e32 v3, v4, v3
	v_sub_f32_e32 v4, v31, v75
	v_exp_f32_e32 v81, v4
	v_sub_f32_e32 v4, v15, v75
	v_exp_f32_e32 v90, v4
	v_sub_f32_e32 v4, v32, v75
	v_exp_f32_e32 v91, v4
	v_sub_f32_e32 v4, v16, v75
	v_exp_f32_e32 v92, v4
	v_sub_f32_e32 v2, 0xf149f2ca, v75
	v_add_f32_e32 v4, v81, v90
	v_add_f32_e32 v3, v4, v3
	v_exp_f32_e32 v2, v2
	v_add_f32_e32 v4, v91, v92
	v_add_f32_e32 v76, v4, v3
	ds_bpermute_b32 v77, v197, v76
	v_cmp_gt_f32_e32 vcc, v17, v79
	s_cmp_lg_u64 vcc, 0
	v_mul_f32_e32 v78, 0, v2
	s_cselect_b64 vcc, -1, 0
	v_cndmask_b32_e32 v2, 0, v78, vcc
	v_mov_b32_e32 v3, v2
	v_mov_b32_e32 v4, v2
	v_mov_b32_e32 v5, v2
	v_mov_b32_e32 v6, v2
	v_mov_b32_e32 v7, v2
	v_mov_b32_e32 v8, v2
	v_mov_b32_e32 v9, v2
	v_mov_b32_e32 v10, v2
	v_mov_b32_e32 v11, v2
	v_mov_b32_e32 v12, v2
	v_mov_b32_e32 v13, v2
	v_mov_b32_e32 v14, v2
	v_mov_b32_e32 v15, v2
	v_mov_b32_e32 v16, v2
	v_mov_b32_e32 v17, v2
	ds_read_b64_tr_b16 v[44:45], v89 offset:12288
	ds_read_b64_tr_b16 v[46:47], v89 offset:13824
	ds_read_b64_tr_b16 v[50:51], v89 offset:13888
	ds_read_b64_tr_b16 v[48:49], v89 offset:12352
	v_cvt_pk_bf16_f32 v52, v33, v18
	v_cvt_pk_bf16_f32 v53, v19, v20
	v_cvt_pk_bf16_f32 v54, v21, v22
	v_cvt_pk_bf16_f32 v55, v23, v24
	s_nop 1
	v_mfma_f32_32x32x16_bf16 v[18:33], v[34:37], v[52:55], v[2:17]
	v_mfma_f32_32x32x16_bf16 v[2:17], v[38:41], v[52:55], v[2:17]
	ds_read_b64_tr_b16 v[34:35], v89 offset:15360
	ds_read_b64_tr_b16 v[36:37], v89 offset:16896
	ds_read_b64_tr_b16 v[40:41], v89 offset:16960
	ds_read_b64_tr_b16 v[38:39], v89 offset:15424
	v_cvt_pk_bf16_f32 v52, v63, v65
	v_cvt_pk_bf16_f32 v53, v67, v69
	v_cvt_pk_bf16_f32 v54, v71, v73
	v_cvt_pk_bf16_f32 v55, v81, v91
	s_waitcnt lgkmcnt(6)
	s_nop 0
	v_mfma_f32_32x32x16_bf16 v[18:33], v[44:47], v[52:55], v[18:33]
	s_waitcnt lgkmcnt(4)
	v_mfma_f32_32x32x16_bf16 v[2:17], v[48:51], v[52:55], v[2:17]
	ds_read_b64_tr_b16 v[44:45], v89 offset:18432
	ds_read_b64_tr_b16 v[46:47], v89 offset:19968
	ds_read_b64_tr_b16 v[50:51], v89 offset:20032
	ds_read_b64_tr_b16 v[48:49], v89 offset:18496
	v_cvt_pk_bf16_f32 v52, v43, v56
	v_cvt_pk_bf16_f32 v53, v57, v58
	v_cvt_pk_bf16_f32 v54, v59, v60
	v_cvt_pk_bf16_f32 v55, v61, v62
	s_waitcnt lgkmcnt(6)
	s_nop 0
	v_mfma_f32_32x32x16_bf16 v[18:33], v[34:37], v[52:55], v[18:33]
	s_waitcnt lgkmcnt(4)
	v_mfma_f32_32x32x16_bf16 v[2:17], v[38:41], v[52:55], v[2:17]
	v_cvt_pk_bf16_f32 v34, v64, v66
	v_cvt_pk_bf16_f32 v35, v68, v70
	v_cvt_pk_bf16_f32 v36, v72, v80
	v_cvt_pk_bf16_f32 v37, v90, v92
	s_waitcnt lgkmcnt(2)
	s_nop 0
	v_mfma_f32_32x32x16_bf16 v[18:33], v[44:47], v[34:37], v[18:33]
	s_waitcnt lgkmcnt(0)
	v_mfma_f32_32x32x16_bf16 v[2:17], v[48:51], v[34:37], v[2:17]
	ds_read_b128 v[34:37], v42 offset:21504
	ds_read_b128 v[66:69], v42 offset:21536
	ds_read_b128 v[38:41], v42 offset:26112
	ds_read_b128 v[70:73], v42 offset:26144
	ds_read_b128 v[90:93], v42 offset:21568
	ds_read_b128 v[94:97], v42 offset:21600
	ds_read_b128 v[114:117], v42 offset:26176
	ds_read_b128 v[118:121], v42 offset:26208
	s_waitcnt lgkmcnt(7)
	v_mfma_f32_32x32x16_bf16 v[50:65], v[34:37], v[98:101], 0
	s_waitcnt lgkmcnt(5)
	v_mfma_f32_32x32x16_bf16 v[34:49], v[38:41], v[98:101], 0
	v_mfma_f32_32x32x16_bf16 v[50:65], v[66:69], v[102:105], v[50:65]
	s_waitcnt lgkmcnt(4)
	v_mfma_f32_32x32x16_bf16 v[34:49], v[70:73], v[102:105], v[34:49]
	s_waitcnt lgkmcnt(3)
	v_mfma_f32_32x32x16_bf16 v[50:65], v[90:93], v[106:109], v[50:65]
	ds_read_b64_tr_b16 v[66:67], v89 offset:30720
	ds_read_b64_tr_b16 v[68:69], v89 offset:32256
	ds_read_b64_tr_b16 v[72:73], v89 offset:32320
	ds_read_b64_tr_b16 v[70:71], v89 offset:30784
	v_add_u32_e32 v81, 0xfffffbe1, v74
	v_cmp_lt_i32_e64 s[8:9], -1, v81
	v_cmp_gt_i32_e32 vcc, 16, v0
	s_and_b64 s[10:11], vcc, s[8:9]
	v_mov_b32_e32 v80, 0xf149f2ca
	s_waitcnt lgkmcnt(5)
	v_mfma_f32_32x32x16_bf16 v[34:49], v[114:117], v[106:109], v[34:49]
	v_mfma_f32_32x32x16_bf16 v[50:65], v[94:97], v[110:113], v[50:65]
	s_waitcnt lgkmcnt(4)
	v_mfma_f32_32x32x16_bf16 v[34:49], v[118:121], v[110:113], v[34:49]
	v_min_u32_e32 v210, 0x7f, v81
	v_lshl_add_u32 v210, v210, 2, s3
	v_cndmask_b32_e64 v210, v242, v210, s[10:11]
	ds_read_b32 v210, v210
	s_nop 6
	v_add_u32_e32 v150, 0xfffff9e1, v74
	v_cmp_lt_i32_e64 s[10:11], -1, v150
	v_cmp_gt_i32_e64 s[8:9], 8, v0
	s_and_b64 s[12:13], s[8:9], s[10:11]
	v_min_u32_e32 v211, 0x7f, v150
	v_lshl_add_u32 v211, v211, 2, s3
	v_cndmask_b32_e64 v211, v242, v211, s[12:13]
	ds_read_b32 v211, v211
	v_add_u32_e32 v81, 0xfffffbd1, v74
	v_cmp_lt_i32_e64 s[10:11], -1, v81
	s_and_b64 s[12:13], vcc, s[10:11]
	v_min_u32_e32 v212, 0x7f, v81
	v_lshl_add_u32 v212, v212, 2, s3
	v_cndmask_b32_e64 v212, v242, v212, s[12:13]
	ds_read_b32 v212, v212
	v_add_u32_e32 v151, 0xfffff9d1, v74
	v_cmp_lt_i32_e64 s[10:11], -1, v151
	s_and_b64 s[12:13], s[8:9], s[10:11]
	v_min_u32_e32 v213, 0x7f, v151
	v_lshl_add_u32 v213, v213, 2, s3
	v_cndmask_b32_e64 v213, v242, v213, s[12:13]
	ds_read_b32 v213, v213
	v_add_u32_e32 v81, 0xfffffbc1, v74
	v_cmp_lt_i32_e64 s[10:11], -1, v81
	s_and_b64 s[12:13], vcc, s[10:11]
	v_min_u32_e32 v214, 0x7f, v81
	v_lshl_add_u32 v214, v214, 2, s3
	v_cndmask_b32_e64 v214, v242, v214, s[12:13]
	ds_read_b32 v214, v214
	v_add_u32_e32 v152, 0xfffff9c1, v74
	v_cmp_lt_i32_e32 vcc, -1, v152
	s_and_b64 s[10:11], s[8:9], vcc
	v_min_u32_e32 v215, 0x7f, v152
	v_lshl_add_u32 v215, v215, 2, s3
	v_cndmask_b32_e64 v215, v242, v215, s[10:11]
	ds_read_b32 v215, v215
	v_add_u32_e32 v81, 0xfffffbb1, v74
	v_cmp_lt_i32_e32 vcc, -1, v81
	v_cmp_gt_i32_e64 s[8:9], 15, v0
	s_and_b64 s[10:11], s[8:9], vcc
	v_min_u32_e32 v216, 0x7f, v81
	v_lshl_add_u32 v216, v216, 2, s3
	v_cndmask_b32_e64 v216, v242, v216, s[10:11]
	ds_read_b32 v216, v216
	v_add_u32_e32 v153, 0xfffff9b1, v74
	v_cmp_lt_i32_e32 vcc, -1, v153
	v_cmp_gt_i32_e64 s[8:9], 7, v0
	s_and_b64 s[10:11], s[8:9], vcc
	v_min_u32_e32 v217, 0x7f, v153
	v_lshl_add_u32 v217, v217, 2, s3
	v_cndmask_b32_e64 v217, v242, v217, s[10:11]
	ds_read_b32 v217, v217
	v_add_u32_e32 v81, 0xfffffb61, v74
	v_cmp_lt_i32_e64 s[8:9], -1, v81
	v_cmp_gt_i32_e32 vcc, 14, v0
	s_and_b64 s[10:11], vcc, s[8:9]
	v_min_u32_e32 v218, 0x7f, v81
	v_lshl_add_u32 v218, v218, 2, s3
	v_cndmask_b32_e64 v218, v242, v218, s[10:11]
	ds_read_b32 v218, v218
	v_add_u32_e32 v154, 0xfffff961, v74
	v_cmp_lt_i32_e64 s[10:11], -1, v154
	v_cmp_gt_i32_e64 s[8:9], 6, v0
	s_and_b64 s[12:13], s[8:9], s[10:11]
	v_min_u32_e32 v219, 0x7f, v154
	v_lshl_add_u32 v219, v219, 2, s3
	v_cndmask_b32_e64 v219, v242, v219, s[12:13]
	ds_read_b32 v219, v219
	v_add_u32_e32 v81, 0xfffffb51, v74
	v_cmp_lt_i32_e64 s[10:11], -1, v81
	s_and_b64 s[12:13], vcc, s[10:11]
	v_min_u32_e32 v220, 0x7f, v81
	v_lshl_add_u32 v220, v220, 2, s3
	v_cndmask_b32_e64 v220, v242, v220, s[12:13]
	ds_read_b32 v220, v220
	v_add_u32_e32 v155, 0xfffff951, v74
	v_cmp_lt_i32_e64 s[10:11], -1, v155
	s_and_b64 s[12:13], s[8:9], s[10:11]
	v_min_u32_e32 v221, 0x7f, v155
	v_lshl_add_u32 v221, v221, 2, s3
	v_cndmask_b32_e64 v221, v242, v221, s[12:13]
	ds_read_b32 v221, v221
	v_add_u32_e32 v81, 0xfffffb41, v74
	v_cmp_lt_i32_e64 s[10:11], -1, v81
	s_and_b64 s[12:13], vcc, s[10:11]
	v_min_u32_e32 v222, 0x7f, v81
	v_lshl_add_u32 v222, v222, 2, s3
	v_cndmask_b32_e64 v222, v242, v222, s[12:13]
	ds_read_b32 v222, v222
	v_add_u32_e32 v156, 0xfffff941, v74
	v_cmp_lt_i32_e32 vcc, -1, v156
	s_and_b64 s[10:11], s[8:9], vcc
	v_min_u32_e32 v223, 0x7f, v156
	v_lshl_add_u32 v223, v223, 2, s3
	v_cndmask_b32_e64 v223, v242, v223, s[10:11]
	ds_read_b32 v223, v223
	v_add_u32_e32 v81, 0xfffffb31, v74
	v_cmp_lt_i32_e32 vcc, -1, v81
	v_cmp_gt_i32_e64 s[8:9], 13, v0
	s_and_b64 s[10:11], s[8:9], vcc
	v_min_u32_e32 v224, 0x7f, v81
	v_lshl_add_u32 v224, v224, 2, s3
	v_cndmask_b32_e64 v224, v242, v224, s[10:11]
	ds_read_b32 v224, v224
	v_add_u32_e32 v157, 0xfffff931, v74
	v_cmp_lt_i32_e32 vcc, -1, v157
	v_cmp_gt_i32_e64 s[8:9], 5, v0
	s_and_b64 s[10:11], s[8:9], vcc
	v_min_u32_e32 v225, 0x7f, v157
	v_lshl_add_u32 v225, v225, 2, s3
	v_cndmask_b32_e64 v225, v242, v225, s[10:11]
	ds_read_b32 v225, v225
	v_add_u32_e32 v81, 0xfffffae1, v74
	v_cmp_lt_i32_e64 s[8:9], -1, v81
	v_cmp_gt_i32_e32 vcc, 12, v0
	s_and_b64 s[10:11], vcc, s[8:9]
	v_min_u32_e32 v226, 0x7f, v81
	v_lshl_add_u32 v226, v226, 2, s3
	v_cndmask_b32_e64 v226, v242, v226, s[10:11]
	ds_read_b32 v226, v226
	v_add_u32_e32 v158, 0xfffff8e1, v74
	v_cmp_lt_i32_e64 s[10:11], -1, v158
	v_cmp_gt_i32_e64 s[8:9], 4, v0
	s_and_b64 s[12:13], s[8:9], s[10:11]
	v_min_u32_e32 v227, 0x7f, v158
	v_lshl_add_u32 v227, v227, 2, s3
	v_cndmask_b32_e64 v227, v242, v227, s[12:13]
	ds_read_b32 v227, v227
	v_add_u32_e32 v81, 0xfffffad1, v74
	v_cmp_lt_i32_e64 s[10:11], -1, v81
	s_and_b64 s[12:13], vcc, s[10:11]
	v_min_u32_e32 v228, 0x7f, v81
	v_lshl_add_u32 v228, v228, 2, s3
	v_cndmask_b32_e64 v228, v242, v228, s[12:13]
	ds_read_b32 v228, v228
	v_add_u32_e32 v159, 0xfffff8d1, v74
	v_cmp_lt_i32_e64 s[10:11], -1, v159
	s_and_b64 s[12:13], s[8:9], s[10:11]
	v_min_u32_e32 v229, 0x7f, v159
	v_lshl_add_u32 v229, v229, 2, s3
	v_cndmask_b32_e64 v229, v242, v229, s[12:13]
	ds_read_b32 v229, v229
	v_add_u32_e32 v81, 0xfffffac1, v74
	v_cmp_lt_i32_e64 s[10:11], -1, v81
	s_and_b64 s[12:13], vcc, s[10:11]
	v_min_u32_e32 v230, 0x7f, v81
	v_lshl_add_u32 v230, v230, 2, s3
	v_cndmask_b32_e64 v230, v242, v230, s[12:13]
	ds_read_b32 v230, v230
	v_add_u32_e32 v160, 0xfffff8c1, v74
	v_cmp_lt_i32_e32 vcc, -1, v160
	s_and_b64 s[10:11], s[8:9], vcc
	v_min_u32_e32 v231, 0x7f, v160
	v_lshl_add_u32 v231, v231, 2, s3
	v_cndmask_b32_e64 v231, v242, v231, s[10:11]
	ds_read_b32 v231, v231
	v_add_u32_e32 v81, 0xfffffab1, v74
	v_cmp_lt_i32_e32 vcc, -1, v81
	v_cmp_gt_i32_e64 s[8:9], 11, v0
	s_and_b64 s[10:11], s[8:9], vcc
	v_min_u32_e32 v232, 0x7f, v81
	v_lshl_add_u32 v232, v232, 2, s3
	v_cndmask_b32_e64 v232, v242, v232, s[10:11]
	ds_read_b32 v232, v232
	v_add_u32_e32 v161, 0xfffff8b1, v74
	v_cmp_lt_i32_e32 vcc, -1, v161
	v_cmp_gt_i32_e64 s[8:9], 3, v0
	s_and_b64 s[10:11], s[8:9], vcc
	v_min_u32_e32 v233, 0x7f, v161
	v_lshl_add_u32 v233, v233, 2, s3
	v_cndmask_b32_e64 v233, v242, v233, s[10:11]
	ds_read_b32 v233, v233
	v_add_u32_e32 v81, 0xfffffa61, v74
	v_cmp_lt_i32_e64 s[8:9], -1, v81
	v_cmp_gt_i32_e32 vcc, 10, v0
	s_and_b64 s[10:11], vcc, s[8:9]
	v_min_u32_e32 v234, 0x7f, v81
	v_lshl_add_u32 v234, v234, 2, s3
	v_cndmask_b32_e64 v234, v242, v234, s[10:11]
	ds_read_b32 v234, v234
	v_add_u32_e32 v162, 0xfffff861, v74
	v_cmp_lt_i32_e64 s[10:11], -1, v162
	v_cmp_gt_i32_e64 s[8:9], 2, v0
	s_and_b64 s[12:13], s[8:9], s[10:11]
	v_min_u32_e32 v235, 0x7f, v162
	v_lshl_add_u32 v235, v235, 2, s3
	v_cndmask_b32_e64 v235, v242, v235, s[12:13]
	ds_read_b32 v235, v235
	v_add_u32_e32 v81, 0xfffffa51, v74
	v_cmp_lt_i32_e64 s[10:11], -1, v81
	s_and_b64 s[12:13], vcc, s[10:11]
	v_min_u32_e32 v236, 0x7f, v81
	v_lshl_add_u32 v236, v236, 2, s3
	v_cndmask_b32_e64 v236, v242, v236, s[12:13]
	ds_read_b32 v236, v236
	v_add_u32_e32 v163, 0xfffff851, v74
	v_cmp_lt_i32_e64 s[10:11], -1, v163
	s_and_b64 s[12:13], s[8:9], s[10:11]
	v_min_u32_e32 v237, 0x7f, v163
	v_lshl_add_u32 v237, v237, 2, s3
	v_cndmask_b32_e64 v237, v242, v237, s[12:13]
	ds_read_b32 v237, v237
	v_add_u32_e32 v81, 0xfffffa41, v74
	v_cmp_lt_i32_e64 s[10:11], -1, v81
	s_and_b64 s[12:13], vcc, s[10:11]
	v_min_u32_e32 v238, 0x7f, v81
	v_lshl_add_u32 v238, v238, 2, s3
	v_cndmask_b32_e64 v238, v242, v238, s[12:13]
	ds_read_b32 v238, v238
	v_add_u32_e32 v164, 0xfffff841, v74
	v_cmp_lt_i32_e32 vcc, -1, v164
	s_and_b64 s[10:11], s[8:9], vcc
	v_min_u32_e32 v239, 0x7f, v164
	v_lshl_add_u32 v239, v239, 2, s3
	v_cndmask_b32_e64 v239, v242, v239, s[10:11]
	ds_read_b32 v239, v239
	v_add_u32_e32 v81, 0xfffffa31, v74
	v_cmp_lt_i32_e32 vcc, -1, v81
	v_cmp_gt_i32_e64 s[8:9], 9, v0
	s_and_b64 s[10:11], s[8:9], vcc
	v_min_u32_e32 v240, 0x7f, v81
	v_lshl_add_u32 v240, v240, 2, s3
	v_cndmask_b32_e64 v240, v242, v240, s[10:11]
	ds_read_b32 v240, v240
	v_add_u32_e32 v165, 0xfffff831, v74
	v_cmp_lt_i32_e32 vcc, -1, v165
	v_cmp_gt_i32_e64 s[8:9], 1, v0
	s_and_b64 s[10:11], s[8:9], vcc
	v_min_u32_e32 v241, 0x7f, v165
	v_lshl_add_u32 v241, v241, 2, s3
	v_cndmask_b32_e64 v241, v242, v241, s[10:11]
	ds_read_b32 v241, v241
	s_waitcnt lgkmcnt(0)
	v_add_f32_e32 v80, v50, v210
	v_add_f32_e32 v79, v34, v211
	v_add_f32_e32 v50, v51, v212
	v_add_f32_e32 v34, v35, v213
	v_add_f32_e32 v51, v52, v214
	v_add_f32_e32 v35, v36, v215
	v_add_f32_e32 v52, v53, v216
	v_add_f32_e32 v36, v37, v217
	v_add_f32_e32 v53, v54, v218
	v_add_f32_e32 v37, v38, v219
	v_add_f32_e32 v54, v55, v220
	v_add_f32_e32 v38, v39, v221
	v_add_f32_e32 v55, v56, v222
	v_add_f32_e32 v39, v40, v223
	v_add_f32_e32 v56, v57, v224
	v_add_f32_e32 v40, v41, v225
	v_add_f32_e32 v57, v58, v226
	v_add_f32_e32 v41, v42, v227
	v_add_f32_e32 v58, v59, v228
	v_add_f32_e32 v42, v43, v229
	v_add_f32_e32 v59, v60, v230
	v_add_f32_e32 v43, v44, v231
	v_add_f32_e32 v60, v61, v232
	v_add_f32_e32 v44, v45, v233
	v_add_f32_e32 v61, v62, v234
	v_add_f32_e32 v45, v46, v235
	v_add_f32_e32 v62, v63, v236
	v_add_f32_e32 v46, v47, v237
	v_add_f32_e32 v63, v64, v238
	v_add_f32_e32 v47, v48, v239
	v_add_f32_e32 v64, v65, v240
	v_add_f32_e32 v48, v49, v241
	v_max3_f32 v0, v191, v80, v79
	v_max_f32_e32 v65, v75, v75
	v_max3_f32 v0, v0, v50, v34
	v_max3_f32 v0, v0, v51, v35
	v_max3_f32 v0, v0, v52, v36
	v_max3_f32 v0, v0, v53, v37
	v_max3_f32 v0, v0, v54, v38
	v_max3_f32 v0, v0, v55, v39
	v_max3_f32 v0, v0, v56, v40
	v_max3_f32 v0, v0, v57, v41
	v_max3_f32 v0, v0, v58, v42
	v_max3_f32 v0, v0, v59, v43
	v_max3_f32 v0, v0, v60, v44
	v_max3_f32 v0, v0, v61, v45
	v_max3_f32 v0, v0, v62, v46
	v_max3_f32 v0, v0, v63, v47
	v_max3_f32 v0, v0, v64, v48
	v_mov_b32_e32 v49, v0
	s_nop 1
	v_permlane32_swap_b32 v49, v0
	v_max_f32_e32 v0, v0, v0
	s_waitcnt lgkmcnt(0)
	v_max_f32_e32 v49, v49, v49
	v_max_f32_e32 v49, v0, v49
	v_max_f32_e32 v118, v65, v49
	v_sub_f32_e32 v35, v35, v118
	v_exp_f32_e32 v92, v35
	v_sub_f32_e32 v35, v52, v118
	v_exp_f32_e32 v125, v35
	v_sub_f32_e32 v35, v36, v118
	v_sub_f32_e32 v36, v53, v118
	v_exp_f32_e32 v136, v36
	v_sub_f32_e32 v36, v37, v118
	v_exp_f32_e32 v94, v36
	v_sub_f32_e32 v36, v54, v118
	v_exp_f32_e32 v138, v36
	v_sub_f32_e32 v36, v38, v118
	v_exp_f32_e32 v95, v36
	v_sub_f32_e32 v36, v55, v118
	v_exp_f32_e32 v141, v36
	v_sub_f32_e32 v36, v39, v118
	v_exp_f32_e32 v96, v36
	v_sub_f32_e32 v36, v56, v118
	v_sub_f32_e32 v0, v80, v118
	v_exp_f32_e32 v142, v36
	v_sub_f32_e32 v36, v40, v118
	v_sub_f32_e32 v65, v79, v118
	v_exp_f32_e32 v116, v0
	v_sub_f32_e32 v0, v50, v118
	v_exp_f32_e32 v97, v36
	v_sub_f32_e32 v36, v57, v118
	v_exp_f32_e32 v90, v65
	v_exp_f32_e32 v119, v0
	v_sub_f32_e32 v0, v34, v118
	v_exp_f32_e32 v120, v36
	v_sub_f32_e32 v36, v41, v118
	v_exp_f32_e32 v91, v0
	v_sub_f32_e32 v51, v51, v118
	v_exp_f32_e32 v114, v36
	v_sub_f32_e32 v36, v58, v118
	v_exp_f32_e32 v123, v51
	v_exp_f32_e32 v122, v36
	v_sub_f32_e32 v36, v42, v118
	v_exp_f32_e32 v93, v35
	v_exp_f32_e32 v115, v36
	v_sub_f32_e32 v36, v59, v118
	v_add_f32_e32 v34, v116, v90
	v_exp_f32_e32 v126, v36
	v_sub_f32_e32 v36, v43, v118
	v_add_f32_e32 v34, 0, v34
	v_add_f32_e32 v50, v119, v91
	v_exp_f32_e32 v117, v36
	v_sub_f32_e32 v36, v60, v118
	v_add_f32_e32 v34, v50, v34
	v_add_f32_e32 v35, v123, v92
	v_exp_f32_e32 v128, v36
	v_sub_f32_e32 v36, v44, v118
	v_add_f32_e32 v34, v35, v34
	v_add_f32_e32 v35, v125, v93
	v_exp_f32_e32 v121, v36
	v_sub_f32_e32 v36, v61, v118
	v_add_f32_e32 v34, v35, v34
	v_add_f32_e32 v35, v136, v94
	v_exp_f32_e32 v139, v36
	v_sub_f32_e32 v36, v45, v118
	v_add_f32_e32 v34, v35, v34
	v_add_f32_e32 v35, v138, v95
	v_exp_f32_e32 v124, v36
	v_sub_f32_e32 v36, v62, v118
	v_add_f32_e32 v34, v35, v34
	v_add_f32_e32 v35, v141, v96
	v_exp_f32_e32 v140, v36
	v_sub_f32_e32 v36, v46, v118
	v_add_f32_e32 v34, v35, v34
	v_add_f32_e32 v35, v142, v97
	v_exp_f32_e32 v127, v36
	v_sub_f32_e32 v36, v63, v118
	v_add_f32_e32 v34, v35, v34
	v_add_f32_e32 v35, v120, v114
	v_exp_f32_e32 v143, v36
	v_sub_f32_e32 v36, v47, v118
	v_add_f32_e32 v34, v35, v34
	v_add_f32_e32 v35, v122, v115
	v_exp_f32_e32 v129, v36
	v_sub_f32_e32 v36, v64, v118
	v_add_f32_e32 v34, v35, v34
	v_add_f32_e32 v35, v126, v117
	v_exp_f32_e32 v144, v36
	v_sub_f32_e32 v36, v48, v118
	v_add_f32_e32 v34, v35, v34
	v_add_f32_e32 v35, v128, v121
	v_exp_f32_e32 v137, v36
	v_add_f32_e32 v34, v35, v34
	v_add_f32_e32 v35, v139, v124
	v_add_f32_e32 v34, v35, v34
	v_add_f32_e32 v35, v140, v127
	v_add_f32_e32 v34, v35, v34
	v_add_f32_e32 v35, v143, v129
	v_add_f32_e32 v34, v35, v34
	v_add_f32_e32 v35, v144, v137
	v_add_f32_e32 v34, v35, v34
	v_sub_f32_e32 v0, v75, v118
	ds_bpermute_b32 v35, v197, v34
	v_exp_f32_e32 v0, v0
	v_cmp_gt_f32_e32 vcc, v49, v75
	s_cbranch_vccz .LBB0_1382
	v_pk_mul_f32 v[32:33], v[32:33], v[0:1] op_sel_hi:[1,0]
	v_pk_mul_f32 v[30:31], v[30:31], v[0:1] op_sel_hi:[1,0]
	v_pk_mul_f32 v[28:29], v[28:29], v[0:1] op_sel_hi:[1,0]
	v_pk_mul_f32 v[26:27], v[26:27], v[0:1] op_sel_hi:[1,0]
	v_pk_mul_f32 v[24:25], v[24:25], v[0:1] op_sel_hi:[1,0]
	v_pk_mul_f32 v[22:23], v[22:23], v[0:1] op_sel_hi:[1,0]
	v_pk_mul_f32 v[20:21], v[20:21], v[0:1] op_sel_hi:[1,0]
	v_pk_mul_f32 v[18:19], v[18:19], v[0:1] op_sel_hi:[1,0]
	v_pk_mul_f32 v[16:17], v[16:17], v[0:1] op_sel_hi:[1,0]
	v_pk_mul_f32 v[14:15], v[14:15], v[0:1] op_sel_hi:[1,0]
	v_pk_mul_f32 v[12:13], v[12:13], v[0:1] op_sel_hi:[1,0]
	v_pk_mul_f32 v[10:11], v[10:11], v[0:1] op_sel_hi:[1,0]
	v_pk_mul_f32 v[8:9], v[8:9], v[0:1] op_sel_hi:[1,0]
	v_pk_mul_f32 v[6:7], v[6:7], v[0:1] op_sel_hi:[1,0]
	v_pk_mul_f32 v[4:5], v[4:5], v[0:1] op_sel_hi:[1,0]
	v_pk_mul_f32 v[2:3], v[2:3], v[0:1] op_sel_hi:[1,0]

.LBB0_1502:
	v_max3_f32 v34, v191, v66, v82
	s_nop 8
	v_max_f32_e32 v36, v177, v177
	v_max3_f32 v34, v34, v67, v83
	v_max3_f32 v34, v34, v68, v84
	v_max3_f32 v34, v34, v69, v85
	v_max3_f32 v34, v34, v70, v86
	v_max3_f32 v34, v34, v71, v87
	v_max3_f32 v34, v34, v72, v88
	v_max3_f32 v34, v34, v73, v89
	v_max3_f32 v34, v34, v74, v90
	v_max3_f32 v34, v34, v75, v91
	v_max3_f32 v34, v34, v76, v92
	v_max3_f32 v34, v34, v77, v93
	v_max3_f32 v34, v34, v78, v94
	v_max3_f32 v34, v34, v79, v95
	v_max3_f32 v34, v34, v80, v96
	v_max3_f32 v34, v34, v81, v97
	v_mov_b32_e32 v35, v34
	s_nop 1
	v_permlane32_swap_b32 v35, v34
	v_max_f32_e32 v34, v34, v34
	s_waitcnt lgkmcnt(0)
	v_max_f32_e32 v35, v35, v35
	v_max_f32_e32 v174, v34, v35
	v_max_f32_e32 v35, v36, v174
	v_sub_f32_e32 v34, v66, v35
	v_sub_f32_e32 v36, v82, v35
	v_exp_f32_e32 v53, v34
	v_sub_f32_e32 v34, v67, v35
	v_exp_f32_e32 v36, v36
	v_exp_f32_e32 v55, v34
	v_sub_f32_e32 v34, v83, v35
	v_sub_f32_e32 v40, v68, v35
	v_exp_f32_e32 v39, v34
	v_exp_f32_e32 v58, v40
	v_sub_f32_e32 v40, v84, v35
	v_sub_f32_e32 v41, v69, v35
	v_exp_f32_e32 v40, v40
	v_exp_f32_e32 v60, v41
	v_sub_f32_e32 v41, v85, v35
	v_sub_f32_e32 v42, v70, v35
	v_sub_f32_e32 v44, v72, v35
	v_exp_f32_e32 v41, v41
	v_exp_f32_e32 v62, v42
	v_sub_f32_e32 v42, v86, v35
	v_sub_f32_e32 v43, v71, v35
	v_exp_f32_e32 v66, v44
	v_sub_f32_e32 v44, v88, v35
	v_add_f32_e32 v37, v53, v36
	v_exp_f32_e32 v42, v42
	v_exp_f32_e32 v64, v43
	v_sub_f32_e32 v43, v87, v35
	v_exp_f32_e32 v45, v44
	v_sub_f32_e32 v44, v73, v35
	v_add_f32_e32 v37, 0, v37
	v_add_f32_e32 v38, v55, v39
	v_exp_f32_e32 v43, v43
	v_exp_f32_e32 v68, v44
	v_sub_f32_e32 v44, v89, v35
	v_add_f32_e32 v37, v38, v37
	v_add_f32_e32 v38, v58, v40
	v_exp_f32_e32 v47, v44
	v_sub_f32_e32 v44, v74, v35
	v_add_f32_e32 v37, v38, v37
	v_add_f32_e32 v38, v60, v41
	v_exp_f32_e32 v52, v44
	v_sub_f32_e32 v44, v90, v35
	v_sub_f32_e32 v46, v75, v35
	v_add_f32_e32 v37, v38, v37
	v_add_f32_e32 v38, v62, v42
	v_exp_f32_e32 v44, v44
	v_exp_f32_e32 v56, v46
	v_sub_f32_e32 v46, v91, v35
	v_sub_f32_e32 v48, v76, v35
	v_add_f32_e32 v37, v38, v37
	v_add_f32_e32 v38, v64, v43
	v_exp_f32_e32 v46, v46
	v_exp_f32_e32 v59, v48
	v_sub_f32_e32 v48, v92, v35
	v_sub_f32_e32 v49, v77, v35
	v_add_f32_e32 v37, v38, v37
	v_add_f32_e32 v38, v66, v45
	v_exp_f32_e32 v48, v48
	v_exp_f32_e32 v61, v49
	v_sub_f32_e32 v49, v93, v35
	v_sub_f32_e32 v50, v78, v35
	v_add_f32_e32 v37, v38, v37
	v_add_f32_e32 v38, v68, v47
	v_exp_f32_e32 v49, v49
	v_exp_f32_e32 v63, v50
	v_sub_f32_e32 v50, v94, v35
	v_sub_f32_e32 v51, v79, v35
	v_add_f32_e32 v37, v38, v37
	v_add_f32_e32 v38, v52, v44
	v_exp_f32_e32 v50, v50
	v_exp_f32_e32 v65, v51
	v_sub_f32_e32 v51, v95, v35
	v_sub_f32_e32 v54, v80, v35
	v_add_f32_e32 v37, v38, v37
	v_add_f32_e32 v38, v56, v46
	v_exp_f32_e32 v51, v51
	v_exp_f32_e32 v67, v54
	v_sub_f32_e32 v54, v96, v35
	v_sub_f32_e32 v57, v81, v35
	v_add_f32_e32 v37, v38, v37
	v_add_f32_e32 v38, v59, v48
	v_exp_f32_e32 v54, v54
	v_exp_f32_e32 v69, v57
	v_sub_f32_e32 v57, v97, v35
	v_add_f32_e32 v37, v38, v37
	v_add_f32_e32 v38, v61, v49
	v_exp_f32_e32 v57, v57
	v_add_f32_e32 v37, v38, v37
	v_add_f32_e32 v38, v63, v50
	v_add_f32_e32 v37, v38, v37
	v_add_f32_e32 v38, v65, v51
	v_add_f32_e32 v37, v38, v37
	v_add_f32_e32 v38, v67, v54
	v_add_f32_e32 v37, v38, v37
	v_add_f32_e32 v38, v69, v57
	v_add_f32_e32 v37, v38, v37
	v_sub_f32_e32 v34, v177, v35
	ds_bpermute_b32 v38, v197, v37
	v_exp_f32_e32 v34, v34
	v_cmp_gt_f32_e32 vcc, v174, v177
	s_cbranch_vccz .LBB0_1504
	v_pk_mul_f32 v[16:17], v[16:17], v[34:35] op_sel_hi:[1,0]
	v_pk_mul_f32 v[14:15], v[14:15], v[34:35] op_sel_hi:[1,0]
	v_pk_mul_f32 v[12:13], v[12:13], v[34:35] op_sel_hi:[1,0]
	v_pk_mul_f32 v[10:11], v[10:11], v[34:35] op_sel_hi:[1,0]
	v_pk_mul_f32 v[8:9], v[8:9], v[34:35] op_sel_hi:[1,0]
	v_pk_mul_f32 v[6:7], v[6:7], v[34:35] op_sel_hi:[1,0]
	v_pk_mul_f32 v[4:5], v[4:5], v[34:35] op_sel_hi:[1,0]
	v_pk_mul_f32 v[2:3], v[2:3], v[34:35] op_sel_hi:[1,0]
	v_pk_mul_f32 v[32:33], v[32:33], v[34:35] op_sel_hi:[1,0]
	v_pk_mul_f32 v[30:31], v[30:31], v[34:35] op_sel_hi:[1,0]
	v_pk_mul_f32 v[28:29], v[28:29], v[34:35] op_sel_hi:[1,0]
	v_pk_mul_f32 v[26:27], v[26:27], v[34:35] op_sel_hi:[1,0]
	v_pk_mul_f32 v[24:25], v[24:25], v[34:35] op_sel_hi:[1,0]
	v_pk_mul_f32 v[22:23], v[22:23], v[34:35] op_sel_hi:[1,0]
	v_pk_mul_f32 v[20:21], v[20:21], v[34:35] op_sel_hi:[1,0]
	v_pk_mul_f32 v[18:19], v[18:19], v[34:35] op_sel_hi:[1,0]

.LBB0_1581:
	v_max3_f32 v0, v191, v66, v82
	s_nop 8
	v_max_f32_e32 v35, v148, v148
	v_max3_f32 v0, v0, v67, v83
	v_max3_f32 v0, v0, v68, v84
	v_max3_f32 v0, v0, v69, v85
	v_max3_f32 v0, v0, v70, v86
	v_max3_f32 v0, v0, v71, v87
	v_max3_f32 v0, v0, v72, v88
	v_max3_f32 v0, v0, v73, v89
	v_max3_f32 v0, v0, v74, v90
	v_max3_f32 v0, v0, v75, v91
	v_max3_f32 v0, v0, v76, v92
	v_max3_f32 v0, v0, v77, v93
	v_max3_f32 v0, v0, v78, v94
	v_max3_f32 v0, v0, v79, v95
	v_max3_f32 v0, v0, v80, v96
	v_max3_f32 v0, v0, v81, v97
	v_mov_b32_e32 v34, v0
	s_nop 1
	v_permlane32_swap_b32 v34, v0
	v_max_f32_e32 v0, v0, v0
	s_waitcnt lgkmcnt(0)
	v_max_f32_e32 v34, v34, v34
	v_max_f32_e32 v221, v0, v34
	v_max_f32_e32 v34, v35, v221
	v_sub_f32_e32 v0, v66, v34
	v_sub_f32_e32 v35, v82, v34
	v_exp_f32_e32 v52, v0
	v_sub_f32_e32 v0, v67, v34
	v_exp_f32_e32 v35, v35
	v_exp_f32_e32 v54, v0
	v_sub_f32_e32 v0, v83, v34
	v_sub_f32_e32 v39, v68, v34
	v_exp_f32_e32 v38, v0
	v_exp_f32_e32 v57, v39
	v_sub_f32_e32 v39, v84, v34
	v_sub_f32_e32 v40, v69, v34
	v_exp_f32_e32 v39, v39
	v_exp_f32_e32 v59, v40
	v_sub_f32_e32 v40, v85, v34
	v_sub_f32_e32 v41, v70, v34
	v_sub_f32_e32 v43, v72, v34
	v_exp_f32_e32 v40, v40
	v_exp_f32_e32 v61, v41
	v_sub_f32_e32 v41, v86, v34
	v_sub_f32_e32 v42, v71, v34
	v_exp_f32_e32 v65, v43
	v_sub_f32_e32 v43, v88, v34
	v_add_f32_e32 v36, v52, v35
	v_exp_f32_e32 v41, v41
	v_exp_f32_e32 v63, v42
	v_sub_f32_e32 v42, v87, v34
	v_exp_f32_e32 v44, v43
	v_sub_f32_e32 v43, v73, v34
	v_add_f32_e32 v36, 0, v36
	v_add_f32_e32 v37, v54, v38
	v_exp_f32_e32 v42, v42
	v_exp_f32_e32 v67, v43
	v_sub_f32_e32 v43, v89, v34
	v_add_f32_e32 v36, v37, v36
	v_add_f32_e32 v37, v57, v39
	v_exp_f32_e32 v46, v43
	v_sub_f32_e32 v43, v74, v34
	v_add_f32_e32 v36, v37, v36
	v_add_f32_e32 v37, v59, v40
	v_exp_f32_e32 v51, v43
	v_sub_f32_e32 v43, v90, v34
	v_sub_f32_e32 v45, v75, v34
	v_add_f32_e32 v36, v37, v36
	v_add_f32_e32 v37, v61, v41
	v_exp_f32_e32 v43, v43
	v_exp_f32_e32 v55, v45
	v_sub_f32_e32 v45, v91, v34
	v_sub_f32_e32 v47, v76, v34
	v_add_f32_e32 v36, v37, v36
	v_add_f32_e32 v37, v63, v42
	v_exp_f32_e32 v45, v45
	v_exp_f32_e32 v58, v47
	v_sub_f32_e32 v47, v92, v34
	v_sub_f32_e32 v48, v77, v34
	v_add_f32_e32 v36, v37, v36
	v_add_f32_e32 v37, v65, v44
	v_exp_f32_e32 v47, v47
	v_exp_f32_e32 v60, v48
	v_sub_f32_e32 v48, v93, v34
	v_sub_f32_e32 v49, v78, v34
	v_add_f32_e32 v36, v37, v36
	v_add_f32_e32 v37, v67, v46
	v_exp_f32_e32 v48, v48
	v_exp_f32_e32 v62, v49
	v_sub_f32_e32 v49, v94, v34
	v_sub_f32_e32 v50, v79, v34
	v_add_f32_e32 v36, v37, v36
	v_add_f32_e32 v37, v51, v43
	v_exp_f32_e32 v49, v49
	v_exp_f32_e32 v64, v50
	v_sub_f32_e32 v50, v95, v34
	v_sub_f32_e32 v53, v80, v34
	v_add_f32_e32 v36, v37, v36
	v_add_f32_e32 v37, v55, v45
	v_exp_f32_e32 v50, v50
	v_exp_f32_e32 v66, v53
	v_sub_f32_e32 v53, v96, v34
	v_sub_f32_e32 v56, v81, v34
	v_add_f32_e32 v36, v37, v36
	v_add_f32_e32 v37, v58, v47
	v_exp_f32_e32 v53, v53
	v_exp_f32_e32 v68, v56
	v_sub_f32_e32 v56, v97, v34
	v_add_f32_e32 v36, v37, v36
	v_add_f32_e32 v37, v60, v48
	v_exp_f32_e32 v56, v56
	v_add_f32_e32 v36, v37, v36
	v_add_f32_e32 v37, v62, v49
	v_add_f32_e32 v36, v37, v36
	v_add_f32_e32 v37, v64, v50
	v_add_f32_e32 v36, v37, v36
	v_add_f32_e32 v37, v66, v53
	v_add_f32_e32 v36, v37, v36
	v_add_f32_e32 v37, v68, v56
	v_add_f32_e32 v36, v37, v36
	v_sub_f32_e32 v0, v148, v34
	ds_bpermute_b32 v37, v197, v36
	v_exp_f32_e32 v0, v0
	v_cmp_gt_f32_e32 vcc, v221, v148
	s_cbranch_vccz .LBB0_1583
	v_pk_mul_f32 v[32:33], v[32:33], v[0:1] op_sel_hi:[1,0]
	v_pk_mul_f32 v[30:31], v[30:31], v[0:1] op_sel_hi:[1,0]
	v_pk_mul_f32 v[28:29], v[28:29], v[0:1] op_sel_hi:[1,0]
	v_pk_mul_f32 v[26:27], v[26:27], v[0:1] op_sel_hi:[1,0]
	v_pk_mul_f32 v[24:25], v[24:25], v[0:1] op_sel_hi:[1,0]
	v_pk_mul_f32 v[22:23], v[22:23], v[0:1] op_sel_hi:[1,0]
	v_pk_mul_f32 v[20:21], v[20:21], v[0:1] op_sel_hi:[1,0]
	v_pk_mul_f32 v[18:19], v[18:19], v[0:1] op_sel_hi:[1,0]
	v_pk_mul_f32 v[16:17], v[16:17], v[0:1] op_sel_hi:[1,0]
	v_pk_mul_f32 v[14:15], v[14:15], v[0:1] op_sel_hi:[1,0]
	v_pk_mul_f32 v[12:13], v[12:13], v[0:1] op_sel_hi:[1,0]
	v_pk_mul_f32 v[10:11], v[10:11], v[0:1] op_sel_hi:[1,0]
	v_pk_mul_f32 v[8:9], v[8:9], v[0:1] op_sel_hi:[1,0]
	v_pk_mul_f32 v[6:7], v[6:7], v[0:1] op_sel_hi:[1,0]
	v_pk_mul_f32 v[4:5], v[4:5], v[0:1] op_sel_hi:[1,0]
	v_pk_mul_f32 v[2:3], v[2:3], v[0:1] op_sel_hi:[1,0]

.LBB0_2633:
	v_max3_f32 v0, v193, v96, v80
	v_max_f32_e32 v208, v207, v207
	v_max3_f32 v0, v0, v97, v81
	v_max3_f32 v0, v0, v98, v82
	v_max3_f32 v0, v0, v99, v83
	v_max3_f32 v0, v0, v100, v84
	v_max3_f32 v0, v0, v101, v85
	v_max3_f32 v0, v0, v102, v86
	v_max3_f32 v0, v0, v103, v87
	v_max3_f32 v0, v0, v104, v88
	v_max3_f32 v0, v0, v105, v89
	v_max3_f32 v0, v0, v106, v90
	v_max3_f32 v0, v0, v107, v91
	v_max3_f32 v0, v0, v108, v92
	v_max3_f32 v0, v0, v109, v93
	v_max3_f32 v0, v0, v110, v94
	v_max3_f32 v0, v0, v111, v95
	v_mov_b32_e32 v15, v0
	s_nop 1
	v_permlane32_swap_b32 v15, v0
	v_max_f32_e32 v0, v0, v0
	s_waitcnt lgkmcnt(0)
	v_max_f32_e32 v15, v15, v15
	v_max_f32_e32 v216, v0, v15
	v_max_f32_e32 v15, v208, v216
	v_sub_f32_e32 v0, v96, v15
	v_sub_f32_e32 v80, v80, v15
	v_exp_f32_e32 v208, v0
	v_sub_f32_e32 v0, v97, v15
	v_exp_f32_e32 v80, v80
	v_exp_f32_e32 v209, v0
	v_sub_f32_e32 v0, v81, v15
	v_exp_f32_e32 v81, v0
	v_sub_f32_e32 v98, v98, v15
	v_sub_f32_e32 v82, v82, v15
	v_exp_f32_e32 v210, v98
	v_exp_f32_e32 v82, v82
	v_add_f32_e32 v96, v208, v80
	v_sub_f32_e32 v98, v99, v15
	v_sub_f32_e32 v83, v83, v15
	v_add_f32_e32 v96, 0, v96
	v_add_f32_e32 v97, v209, v81
	v_exp_f32_e32 v211, v98
	v_exp_f32_e32 v83, v83
	v_add_f32_e32 v96, v97, v96
	v_add_f32_e32 v97, v210, v82
	v_add_f32_e32 v98, v97, v96
	v_sub_f32_e32 v96, v100, v15
	v_sub_f32_e32 v84, v84, v15
	v_exp_f32_e32 v212, v96
	v_exp_f32_e32 v96, v84
	v_sub_f32_e32 v84, v101, v15
	v_add_f32_e32 v99, v211, v83
	v_exp_f32_e32 v213, v84
	v_sub_f32_e32 v84, v85, v15
	v_exp_f32_e32 v97, v84
	v_add_f32_e32 v84, v99, v98
	v_sub_f32_e32 v98, v102, v15
	v_sub_f32_e32 v86, v86, v15
	v_exp_f32_e32 v214, v98
	v_exp_f32_e32 v98, v86
	v_add_f32_e32 v85, v212, v96
	v_add_f32_e32 v84, v85, v84
	v_add_f32_e32 v85, v213, v97
	v_sub_f32_e32 v86, v103, v15
	v_exp_f32_e32 v215, v86
	v_sub_f32_e32 v86, v87, v15
	v_add_f32_e32 v84, v85, v84
	v_add_f32_e32 v85, v214, v98
	v_exp_f32_e32 v99, v86
	v_add_f32_e32 v86, v85, v84
	v_sub_f32_e32 v84, v104, v15
	v_exp_f32_e32 v100, v84
	v_sub_f32_e32 v84, v88, v15
	v_exp_f32_e32 v84, v84
	v_add_f32_e32 v87, v215, v99
	v_sub_f32_e32 v85, v105, v15
	v_add_f32_e32 v86, v87, v86
	v_add_f32_e32 v87, v100, v84
	v_exp_f32_e32 v101, v85
	v_sub_f32_e32 v85, v89, v15
	v_add_f32_e32 v88, v87, v86
	v_sub_f32_e32 v86, v106, v15
	v_exp_f32_e32 v85, v85
	v_exp_f32_e32 v102, v86
	v_sub_f32_e32 v86, v90, v15
	v_exp_f32_e32 v86, v86
	v_add_f32_e32 v89, v101, v85
	v_sub_f32_e32 v87, v107, v15
	v_add_f32_e32 v88, v89, v88
	v_add_f32_e32 v89, v102, v86
	v_exp_f32_e32 v103, v87
	v_sub_f32_e32 v87, v91, v15
	v_add_f32_e32 v90, v89, v88
	v_sub_f32_e32 v88, v108, v15
	v_exp_f32_e32 v87, v87
	v_exp_f32_e32 v104, v88
	v_sub_f32_e32 v88, v92, v15
	v_exp_f32_e32 v88, v88
	v_add_f32_e32 v91, v103, v87
	v_sub_f32_e32 v89, v109, v15
	v_add_f32_e32 v90, v91, v90
	v_add_f32_e32 v91, v104, v88
	v_exp_f32_e32 v92, v89
	v_sub_f32_e32 v89, v93, v15
	v_add_f32_e32 v105, v91, v90
	v_sub_f32_e32 v90, v110, v15
	v_exp_f32_e32 v89, v89
	v_exp_f32_e32 v93, v90
	v_sub_f32_e32 v90, v94, v15
	v_sub_f32_e32 v91, v111, v15
	v_exp_f32_e32 v90, v90
	v_exp_f32_e32 v94, v91
	v_sub_f32_e32 v91, v95, v15
	v_exp_f32_e32 v91, v91
	v_add_f32_e32 v106, v92, v89
	v_add_f32_e32 v95, v106, v105
	v_add_f32_e32 v105, v93, v90
	v_add_f32_e32 v95, v105, v95
	v_add_f32_e32 v105, v94, v91
	v_add_f32_e32 v95, v105, v95
	v_sub_f32_e32 v0, v207, v15
	ds_bpermute_b32 v105, v205, v95
	v_exp_f32_e32 v0, v0
	v_cmp_gt_f32_e32 vcc, v216, v207
	s_cbranch_vccz .LBB0_2635
	v_pk_mul_f32 v[78:79], v[78:79], v[0:1] op_sel_hi:[1,0]
	v_pk_mul_f32 v[76:77], v[76:77], v[0:1] op_sel_hi:[1,0]
	v_pk_mul_f32 v[74:75], v[74:75], v[0:1] op_sel_hi:[1,0]
	v_pk_mul_f32 v[72:73], v[72:73], v[0:1] op_sel_hi:[1,0]
	v_pk_mul_f32 v[70:71], v[70:71], v[0:1] op_sel_hi:[1,0]
	v_pk_mul_f32 v[68:69], v[68:69], v[0:1] op_sel_hi:[1,0]
	v_pk_mul_f32 v[66:67], v[66:67], v[0:1] op_sel_hi:[1,0]
	v_pk_mul_f32 v[64:65], v[64:65], v[0:1] op_sel_hi:[1,0]
	v_pk_mul_f32 v[62:63], v[62:63], v[0:1] op_sel_hi:[1,0]
	v_pk_mul_f32 v[60:61], v[60:61], v[0:1] op_sel_hi:[1,0]
	v_pk_mul_f32 v[58:59], v[58:59], v[0:1] op_sel_hi:[1,0]
	v_pk_mul_f32 v[56:57], v[56:57], v[0:1] op_sel_hi:[1,0]
	v_pk_mul_f32 v[54:55], v[54:55], v[0:1] op_sel_hi:[1,0]
	v_pk_mul_f32 v[52:53], v[52:53], v[0:1] op_sel_hi:[1,0]
	v_pk_mul_f32 v[50:51], v[50:51], v[0:1] op_sel_hi:[1,0]
	v_pk_mul_f32 v[48:49], v[48:49], v[0:1] op_sel_hi:[1,0]
	v_pk_mul_f32 v[46:47], v[46:47], v[0:1] op_sel_hi:[1,0]
	v_pk_mul_f32 v[44:45], v[44:45], v[0:1] op_sel_hi:[1,0]
	v_pk_mul_f32 v[42:43], v[42:43], v[0:1] op_sel_hi:[1,0]
	v_pk_mul_f32 v[40:41], v[40:41], v[0:1] op_sel_hi:[1,0]
	v_pk_mul_f32 v[38:39], v[38:39], v[0:1] op_sel_hi:[1,0]
	v_pk_mul_f32 v[36:37], v[36:37], v[0:1] op_sel_hi:[1,0]
	v_pk_mul_f32 v[34:35], v[34:35], v[0:1] op_sel_hi:[1,0]
	v_pk_mul_f32 v[32:33], v[32:33], v[0:1] op_sel_hi:[1,0]
	v_pk_mul_f32 v[30:31], v[30:31], v[0:1] op_sel_hi:[1,0]
	v_pk_mul_f32 v[28:29], v[28:29], v[0:1] op_sel_hi:[1,0]
	v_pk_mul_f32 v[26:27], v[26:27], v[0:1] op_sel_hi:[1,0]
	v_pk_mul_f32 v[24:25], v[24:25], v[0:1] op_sel_hi:[1,0]
	v_pk_mul_f32 v[22:23], v[22:23], v[0:1] op_sel_hi:[1,0]
	v_pk_mul_f32 v[20:21], v[20:21], v[0:1] op_sel_hi:[1,0]
	v_pk_mul_f32 v[18:19], v[18:19], v[0:1] op_sel_hi:[1,0]
	v_pk_mul_f32 v[16:17], v[16:17], v[0:1] op_sel_hi:[1,0]
